# v71 + globally last leader waits for its invalidate before releasing its XCD (airtight acquire ordering)
# baseline (speedup 1.0000x reference)
.LBB0_163:
	s_or_b64 exec, exec, s[0:1]
	s_and_saveexec_b64 s[0:1], s[2:3]
	s_cbranch_execz .LBB0_165
	v_mov_b32_e32 v0, 1
	global_atomic_add v[6:7], v0, off
	buffer_inv sc1
	s_waitcnt vmcnt(0)

.LBB0_224:
	s_or_b64 exec, exec, s[8:9]
	s_and_saveexec_b64 s[4:5], s[10:11]
	s_cbranch_execz .LBB0_226
	v_mov_b32_e32 v2, 1
	global_atomic_add v[0:1], v2, off
	buffer_inv sc1
	s_waitcnt vmcnt(0)

.LBB0_282:
	s_or_b64 exec, exec, s[8:9]
	s_and_saveexec_b64 s[0:1], s[10:11]
	s_cbranch_execz .LBB0_284
	v_mov_b32_e32 v2, 1
	global_atomic_add v[0:1], v2, off
	buffer_inv sc1
	s_waitcnt vmcnt(0)

.LBB0_360:
	s_or_b64 exec, exec, s[10:11]
	s_and_saveexec_b64 s[4:5], s[12:13]
	s_cbranch_execz .LBB0_362
	v_mov_b32_e32 v2, 1
	global_atomic_add v[0:1], v2, off
	buffer_inv sc1
	s_waitcnt vmcnt(0)

.LBB0_1463:
	s_or_b64 exec, exec, s[10:11]
	s_and_saveexec_b64 s[2:3], s[12:13]
	s_cbranch_execz .LBB0_1465
	v_mov_b32_e32 v2, 1
	global_atomic_add v[0:1], v2, off
	buffer_inv sc1
	s_waitcnt vmcnt(0)
